# th2 plus SwiGLU epilogue: temp-reuse mul pairs packed, per-store address adds moved to SALU, placeholder v_nops dropped (28 fewer VALU slots per wave per unit)
# baseline (speedup 1.0000x reference)
.LBB0_263:
	s_waitcnt lgkmcnt(0)
	v_mul_f32_e32 v152, 0xbfb8aa3b, v174
	v_pk_mul_f32 v[244:245], v[144:145], v[152:153] op_sel_hi:[1,0]
	v_exp_f32_e32 v150, v244
	v_exp_f32_e32 v151, v245
	v_mul_f32_e32 v153, v146, v152
	v_mul_f32_e32 v154, v147, v152
	v_exp_f32_e32 v153, v153
	v_exp_f32_e32 v154, v154
	v_pk_add_f32 v[150:151], v[150:151], 1.0 op_sel_hi:[1,0]
	v_rcp_f32_e32 v150, v150
	v_rcp_f32_e32 v151, v151
	v_pk_mul_f32 v[142:143], v[146:147], v[142:143]
	v_add_f32_e32 v146, 1.0, v153
	v_add_f32_e32 v147, 1.0, v154
	v_rcp_f32_e32 v146, v146
	v_rcp_f32_e32 v147, v147
	v_lshl_or_b32 v149, s47, 7, v193
	v_lshrrev_b32_e32 v246, 4, v172
	v_mul_u32_u24_e32 v246, 0xb0, v246
	v_lshrrev_b32_e32 v247, 5, v149
	v_add_lshl_u32 v246, v246, v247, 10
	v_and_b32_e32 v247, 15, v172
	v_lshl_or_b32 v246, v247, 6, v246
	v_lshrrev_b32_e32 v247, 2, v172
	v_and_b32_e32 v247, 2, v247
	v_bfe_u32 v248, v149, 3, 2
	v_xor_b32_e32 v247, v248, v247
	v_lshl_or_b32 v246, v247, 4, v246
	v_mul_f32_e32 v148, v174, v174
	v_pk_mul_f32 v[140:141], v[144:145], v[140:141]
	v_pk_mul_f32 v[144:145], v[148:149], v[150:151] op_sel_hi:[0,1]
	v_pk_mul_f32 v[140:141], v[140:141], v[144:145]
	v_pk_mul_f32 v[144:145], v[148:149], v[146:147] op_sel_hi:[0,1]
	v_pk_mul_f32 v[146:147], v[136:137], v[152:153] op_sel_hi:[1,0]
	v_exp_f32_e32 v146, v146
	v_exp_f32_e32 v147, v147
	v_pk_mul_f32 v[142:143], v[142:143], v[144:145]
	v_pk_mul_f32 v[134:135], v[138:139], v[134:135]
	v_pk_add_f32 v[144:145], v[146:147], 1.0 op_sel_hi:[1,0]
	v_pk_mul_f32 v[146:147], v[138:139], v[152:153] op_sel_hi:[1,0]
	v_exp_f32_e32 v146, v146
	v_exp_f32_e32 v147, v147
	v_rcp_f32_e32 v144, v144
	v_rcp_f32_e32 v145, v145
	v_pk_add_f32 v[138:139], v[146:147], 1.0 op_sel_hi:[1,0]
	v_rcp_f32_e32 v138, v138
	v_rcp_f32_e32 v139, v139
	v_pk_mul_f32 v[132:133], v[136:137], v[132:133]
	v_pk_mul_f32 v[136:137], v[148:149], v[144:145] op_sel_hi:[0,1]
	v_pk_mul_f32 v[136:137], v[132:133], v[136:137]
	v_pk_mul_f32 v[132:133], v[148:149], v[138:139] op_sel_hi:[0,1]
	s_movk_i32 s6, 0x1600
	v_pk_mul_f32 v[138:139], v[134:135], v[132:133]
	v_cvt_pk_bf16_f32 v134, v136, v137
	v_readlane_b32 s2, v252, 55
	v_cvt_pk_bf16_f32 v132, v140, v141
	v_cvt_pk_bf16_f32 v133, v142, v143
	v_cvt_pk_bf16_f32 v135, v138, v139
	v_readlane_b32 s3, v252, 56
	v_pk_mul_f32 v[126:127], v[130:131], v[126:127]
	v_pk_mul_f32 v[124:125], v[128:129], v[124:125]
	v_pk_mul_f32 v[118:119], v[122:123], v[118:119]
	v_pk_mul_f32 v[116:117], v[120:121], v[116:117]
	v_pk_mul_f32 v[110:111], v[114:115], v[110:111]
	global_store_dwordx4 v246, v[132:135], s[2:3]
	v_pk_mul_f32 v[108:109], v[112:113], v[108:109]
	v_pk_mul_f32 v[102:103], v[106:107], v[102:103]
	v_mul_f32_e32 v133, 0xbfb8aa3b, v175
	v_pk_mul_f32 v[244:245], v[128:129], v[132:133] op_sel:[0,1]
	v_exp_f32_e32 v134, v244
	v_exp_f32_e32 v135, v245
	v_pk_mul_f32 v[136:137], v[130:131], v[132:133] op_sel:[0,1]
	v_exp_f32_e32 v136, v136
	v_exp_f32_e32 v137, v137
	v_pk_add_f32 v[134:135], v[134:135], 1.0 op_sel_hi:[1,0]
	v_rcp_f32_e32 v134, v134
	v_rcp_f32_e32 v135, v135
	v_pk_add_f32 v[130:131], v[136:137], 1.0 op_sel_hi:[1,0]
	v_rcp_f32_e32 v130, v130
	v_rcp_f32_e32 v131, v131
	v_mul_f32_e32 v132, v175, v175
	v_pk_mul_f32 v[128:129], v[132:133], v[134:135] op_sel_hi:[0,1]
	v_pk_mul_f32 v[124:125], v[124:125], v[128:129]
	v_pk_mul_f32 v[128:129], v[132:133], v[130:131] op_sel_hi:[0,1]
	v_pk_mul_f32 v[130:131], v[120:121], v[132:133] op_sel:[0,1]
	v_exp_f32_e32 v130, v130
	v_exp_f32_e32 v131, v131
	v_pk_mul_f32 v[126:127], v[126:127], v[128:129]
	v_pk_mul_f32 v[100:101], v[104:105], v[100:101]
	v_pk_add_f32 v[128:129], v[130:131], 1.0 op_sel_hi:[1,0]
	v_pk_mul_f32 v[130:131], v[122:123], v[132:133] op_sel:[0,1]
	v_exp_f32_e32 v130, v130
	v_exp_f32_e32 v131, v131
	v_rcp_f32_e32 v128, v128
	v_rcp_f32_e32 v129, v129
	v_pk_add_f32 v[122:123], v[130:131], 1.0 op_sel_hi:[1,0]
	v_rcp_f32_e32 v122, v122
	v_rcp_f32_e32 v123, v123
	v_pk_mul_f32 v[120:121], v[132:133], v[128:129] op_sel_hi:[0,1]
	v_pk_mul_f32 v[120:121], v[116:117], v[120:121]
	v_pk_mul_f32 v[94:95], v[98:99], v[94:95]
	v_pk_mul_f32 v[116:117], v[132:133], v[122:123] op_sel_hi:[0,1]
	v_pk_mul_f32 v[122:123], v[118:119], v[116:117]
	v_cvt_pk_bf16_f32 v118, v120, v121
	v_cvt_pk_bf16_f32 v116, v124, v125
	v_cvt_pk_bf16_f32 v117, v126, v127
	v_cvt_pk_bf16_f32 v119, v122, v123
	s_add_u32 s98, s2, 0x2c000
	s_addc_u32 s99, s3, 0
	global_store_dwordx4 v246, v[116:119], s[98:99]
	v_pk_mul_f32 v[92:93], v[96:97], v[92:93]
	v_pk_mul_f32 v[86:87], v[90:91], v[86:87]
	v_mul_f32_e32 v117, 0xbfb8aa3b, v176
	v_pk_mul_f32 v[244:245], v[112:113], v[116:117] op_sel:[0,1]
	v_exp_f32_e32 v118, v244
	v_exp_f32_e32 v119, v245
	v_pk_mul_f32 v[120:121], v[114:115], v[116:117] op_sel:[0,1]
	v_exp_f32_e32 v120, v120
	v_exp_f32_e32 v121, v121
	v_pk_add_f32 v[118:119], v[118:119], 1.0 op_sel_hi:[1,0]
	v_rcp_f32_e32 v118, v118
	v_rcp_f32_e32 v119, v119
	v_pk_add_f32 v[114:115], v[120:121], 1.0 op_sel_hi:[1,0]
	v_rcp_f32_e32 v114, v114
	v_rcp_f32_e32 v115, v115
	v_mul_f32_e32 v116, v176, v176
	v_pk_mul_f32 v[112:113], v[116:117], v[118:119] op_sel_hi:[0,1]
	v_pk_mul_f32 v[108:109], v[108:109], v[112:113]
	v_pk_mul_f32 v[112:113], v[116:117], v[114:115] op_sel_hi:[0,1]
	v_pk_mul_f32 v[114:115], v[104:105], v[116:117] op_sel:[0,1]
	v_exp_f32_e32 v114, v114
	v_exp_f32_e32 v115, v115
	v_pk_mul_f32 v[110:111], v[110:111], v[112:113]
	v_pk_mul_f32 v[84:85], v[88:89], v[84:85]
	v_pk_add_f32 v[112:113], v[114:115], 1.0 op_sel_hi:[1,0]
	v_pk_mul_f32 v[114:115], v[106:107], v[116:117] op_sel:[0,1]
	v_exp_f32_e32 v114, v114
	v_exp_f32_e32 v115, v115
	v_rcp_f32_e32 v112, v112
	v_rcp_f32_e32 v113, v113
	v_pk_add_f32 v[106:107], v[114:115], 1.0 op_sel_hi:[1,0]
	v_rcp_f32_e32 v106, v106
	v_rcp_f32_e32 v107, v107
	v_pk_mul_f32 v[104:105], v[116:117], v[112:113] op_sel_hi:[0,1]
	v_pk_mul_f32 v[104:105], v[100:101], v[104:105]
	v_pk_mul_f32 v[78:79], v[82:83], v[78:79]
	v_pk_mul_f32 v[100:101], v[116:117], v[106:107] op_sel_hi:[0,1]
	v_pk_mul_f32 v[106:107], v[102:103], v[100:101]
	v_cvt_pk_bf16_f32 v102, v104, v105
	v_cvt_pk_bf16_f32 v100, v108, v109
	v_cvt_pk_bf16_f32 v101, v110, v111
	v_cvt_pk_bf16_f32 v103, v106, v107
	s_add_u32 s98, s2, 0x58000
	s_addc_u32 s99, s3, 0
	global_store_dwordx4 v246, v[100:103], s[98:99]
	v_pk_mul_f32 v[76:77], v[80:81], v[76:77]
	v_pk_mul_f32 v[70:71], v[74:75], v[70:71]
	v_mul_f32_e32 v101, 0xbfb8aa3b, v177
	v_pk_mul_f32 v[244:245], v[96:97], v[100:101] op_sel:[0,1]
	v_exp_f32_e32 v102, v244
	v_exp_f32_e32 v103, v245
	v_pk_mul_f32 v[104:105], v[98:99], v[100:101] op_sel:[0,1]
	v_exp_f32_e32 v104, v104
	v_exp_f32_e32 v105, v105
	v_pk_add_f32 v[102:103], v[102:103], 1.0 op_sel_hi:[1,0]
	v_rcp_f32_e32 v102, v102
	v_rcp_f32_e32 v103, v103
	v_pk_add_f32 v[98:99], v[104:105], 1.0 op_sel_hi:[1,0]
	v_rcp_f32_e32 v98, v98
	v_rcp_f32_e32 v99, v99
	v_mul_f32_e32 v100, v177, v177
	v_pk_mul_f32 v[96:97], v[100:101], v[102:103] op_sel_hi:[0,1]
	v_pk_mul_f32 v[92:93], v[92:93], v[96:97]
	v_pk_mul_f32 v[96:97], v[100:101], v[98:99] op_sel_hi:[0,1]
	v_pk_mul_f32 v[98:99], v[88:89], v[100:101] op_sel:[0,1]
	v_exp_f32_e32 v98, v98
	v_exp_f32_e32 v99, v99
	v_pk_mul_f32 v[94:95], v[94:95], v[96:97]
	v_pk_mul_f32 v[68:69], v[72:73], v[68:69]
	v_pk_add_f32 v[96:97], v[98:99], 1.0 op_sel_hi:[1,0]
	v_pk_mul_f32 v[98:99], v[90:91], v[100:101] op_sel:[0,1]
	v_exp_f32_e32 v98, v98
	v_exp_f32_e32 v99, v99
	v_rcp_f32_e32 v96, v96
	v_rcp_f32_e32 v97, v97
	v_pk_add_f32 v[90:91], v[98:99], 1.0 op_sel_hi:[1,0]
	v_rcp_f32_e32 v90, v90
	v_rcp_f32_e32 v91, v91
	v_pk_mul_f32 v[88:89], v[100:101], v[96:97] op_sel_hi:[0,1]
	v_pk_mul_f32 v[88:89], v[84:85], v[88:89]
	v_pk_mul_f32 v[62:63], v[66:67], v[62:63]
	v_pk_mul_f32 v[84:85], v[100:101], v[90:91] op_sel_hi:[0,1]
	v_pk_mul_f32 v[90:91], v[86:87], v[84:85]
	v_cvt_pk_bf16_f32 v86, v88, v89
	v_cvt_pk_bf16_f32 v84, v92, v93
	v_cvt_pk_bf16_f32 v85, v94, v95
	v_cvt_pk_bf16_f32 v87, v90, v91
	s_add_u32 s98, s2, 0x84000
	s_addc_u32 s99, s3, 0
	global_store_dwordx4 v246, v[84:87], s[98:99]
	v_pk_mul_f32 v[60:61], v[64:65], v[60:61]
	v_pk_mul_f32 v[54:55], v[58:59], v[54:55]
	v_mul_f32_e32 v85, 0xbfb8aa3b, v184
	v_pk_mul_f32 v[244:245], v[80:81], v[84:85] op_sel:[0,1]
	v_exp_f32_e32 v86, v244
	v_exp_f32_e32 v87, v245
	v_pk_mul_f32 v[88:89], v[82:83], v[84:85] op_sel:[0,1]
	v_exp_f32_e32 v88, v88
	v_exp_f32_e32 v89, v89
	v_pk_add_f32 v[86:87], v[86:87], 1.0 op_sel_hi:[1,0]
	v_rcp_f32_e32 v86, v86
	v_rcp_f32_e32 v87, v87
	v_pk_add_f32 v[82:83], v[88:89], 1.0 op_sel_hi:[1,0]
	v_rcp_f32_e32 v82, v82
	v_rcp_f32_e32 v83, v83
	v_mul_f32_e32 v84, v184, v184
	v_pk_mul_f32 v[80:81], v[84:85], v[86:87] op_sel_hi:[0,1]
	v_pk_mul_f32 v[76:77], v[76:77], v[80:81]
	v_pk_mul_f32 v[80:81], v[84:85], v[82:83] op_sel_hi:[0,1]
	v_pk_mul_f32 v[82:83], v[72:73], v[84:85] op_sel:[0,1]
	v_exp_f32_e32 v82, v82
	v_exp_f32_e32 v83, v83
	v_pk_mul_f32 v[78:79], v[78:79], v[80:81]
	v_pk_mul_f32 v[52:53], v[56:57], v[52:53]
	v_pk_add_f32 v[80:81], v[82:83], 1.0 op_sel_hi:[1,0]
	v_pk_mul_f32 v[82:83], v[74:75], v[84:85] op_sel:[0,1]
	v_exp_f32_e32 v82, v82
	v_exp_f32_e32 v83, v83
	v_rcp_f32_e32 v80, v80
	v_rcp_f32_e32 v81, v81
	v_pk_add_f32 v[74:75], v[82:83], 1.0 op_sel_hi:[1,0]
	v_rcp_f32_e32 v74, v74
	v_rcp_f32_e32 v75, v75
	v_pk_mul_f32 v[72:73], v[84:85], v[80:81] op_sel_hi:[0,1]
	v_pk_mul_f32 v[72:73], v[68:69], v[72:73]
	v_pk_mul_f32 v[46:47], v[50:51], v[46:47]
	v_pk_mul_f32 v[68:69], v[84:85], v[74:75] op_sel_hi:[0,1]
	v_pk_mul_f32 v[74:75], v[70:71], v[68:69]
	v_cvt_pk_bf16_f32 v70, v72, v73
	v_cvt_pk_bf16_f32 v68, v76, v77
	v_cvt_pk_bf16_f32 v69, v78, v79
	v_cvt_pk_bf16_f32 v71, v74, v75
	s_add_u32 s98, s2, 0x160000
	s_addc_u32 s99, s3, 0
	global_store_dwordx4 v246, v[68:71], s[98:99]
	v_pk_mul_f32 v[44:45], v[48:49], v[44:45]
	v_pk_mul_f32 v[38:39], v[42:43], v[38:39]
	v_mul_f32_e32 v69, 0xbfb8aa3b, v185
	v_pk_mul_f32 v[244:245], v[64:65], v[68:69] op_sel:[0,1]
	v_exp_f32_e32 v70, v244
	v_exp_f32_e32 v71, v245
	v_mul_f32_e32 v73, v66, v69
	v_mul_f32_e32 v74, v67, v69
	v_exp_f32_e32 v73, v73
	v_exp_f32_e32 v74, v74
	v_pk_add_f32 v[70:71], v[70:71], 1.0 op_sel_hi:[1,0]
	v_rcp_f32_e32 v70, v70
	v_rcp_f32_e32 v71, v71
	v_add_f32_e32 v66, 1.0, v73
	v_add_f32_e32 v67, 1.0, v74
	v_rcp_f32_e32 v66, v66
	v_rcp_f32_e32 v67, v67
	v_mul_f32_e32 v68, v185, v185
	v_pk_mul_f32 v[64:65], v[68:69], v[70:71] op_sel_hi:[0,1]
	v_pk_mul_f32 v[60:61], v[60:61], v[64:65]
	v_pk_mul_f32 v[64:65], v[68:69], v[66:67] op_sel_hi:[0,1]
	v_pk_mul_f32 v[66:67], v[56:57], v[68:69] op_sel:[0,1]
	v_exp_f32_e32 v66, v66
	v_exp_f32_e32 v67, v67
	v_pk_mul_f32 v[62:63], v[62:63], v[64:65]
	v_pk_mul_f32 v[36:37], v[40:41], v[36:37]
	v_pk_add_f32 v[64:65], v[66:67], 1.0 op_sel_hi:[1,0]
	v_pk_mul_f32 v[66:67], v[58:59], v[68:69] op_sel:[0,1]
	v_exp_f32_e32 v66, v66
	v_exp_f32_e32 v67, v67
	v_rcp_f32_e32 v64, v64
	v_rcp_f32_e32 v65, v65
	v_pk_add_f32 v[58:59], v[66:67], 1.0 op_sel_hi:[1,0]
	v_rcp_f32_e32 v58, v58
	v_rcp_f32_e32 v59, v59
	v_pk_mul_f32 v[56:57], v[68:69], v[64:65] op_sel_hi:[0,1]
	v_pk_mul_f32 v[56:57], v[52:53], v[56:57]
	v_pk_mul_f32 v[30:31], v[34:35], v[30:31]
	v_pk_mul_f32 v[52:53], v[68:69], v[58:59] op_sel_hi:[0,1]
	v_pk_mul_f32 v[58:59], v[54:55], v[52:53]
	v_cvt_pk_bf16_f32 v52, v60, v61
	v_cvt_pk_bf16_f32 v53, v62, v63
	v_cvt_pk_bf16_f32 v54, v56, v57
	v_cvt_pk_bf16_f32 v55, v58, v59
	s_add_u32 s98, s2, 0x18c000
	s_addc_u32 s99, s3, 0
	global_store_dwordx4 v246, v[52:55], s[98:99]
	v_pk_mul_f32 v[28:29], v[32:33], v[28:29]
	v_pk_mul_f32 v[22:23], v[26:27], v[22:23]
	v_mul_f32_e32 v53, 0xbfb8aa3b, v188
	v_pk_mul_f32 v[244:245], v[48:49], v[52:53] op_sel:[0,1]
	v_exp_f32_e32 v54, v244
	v_exp_f32_e32 v55, v245
	v_pk_mul_f32 v[56:57], v[50:51], v[52:53] op_sel:[0,1]
	v_exp_f32_e32 v56, v56
	v_exp_f32_e32 v57, v57
	v_pk_add_f32 v[54:55], v[54:55], 1.0 op_sel_hi:[1,0]
	v_rcp_f32_e32 v54, v54
	v_rcp_f32_e32 v55, v55
	v_pk_add_f32 v[50:51], v[56:57], 1.0 op_sel_hi:[1,0]
	v_rcp_f32_e32 v50, v50
	v_rcp_f32_e32 v51, v51
	v_mul_f32_e32 v52, v188, v188
	v_pk_mul_f32 v[48:49], v[52:53], v[54:55] op_sel_hi:[0,1]
	v_pk_mul_f32 v[44:45], v[44:45], v[48:49]
	v_pk_mul_f32 v[48:49], v[52:53], v[50:51] op_sel_hi:[0,1]
	v_pk_mul_f32 v[50:51], v[40:41], v[52:53] op_sel:[0,1]
	v_exp_f32_e32 v50, v50
	v_exp_f32_e32 v51, v51
	v_pk_mul_f32 v[46:47], v[46:47], v[48:49]
	v_pk_mul_f32 v[20:21], v[24:25], v[20:21]
	v_pk_add_f32 v[48:49], v[50:51], 1.0 op_sel_hi:[1,0]
	v_pk_mul_f32 v[50:51], v[42:43], v[52:53] op_sel:[0,1]
	v_exp_f32_e32 v50, v50
	v_exp_f32_e32 v51, v51
	v_rcp_f32_e32 v48, v48
	v_rcp_f32_e32 v49, v49
	v_pk_add_f32 v[42:43], v[50:51], 1.0 op_sel_hi:[1,0]
	v_rcp_f32_e32 v42, v42
	v_rcp_f32_e32 v43, v43
	v_pk_mul_f32 v[40:41], v[52:53], v[48:49] op_sel_hi:[0,1]
	v_pk_mul_f32 v[40:41], v[36:37], v[40:41]
	s_andn2_b64 vcc, exec, s[36:37]
	v_pk_mul_f32 v[36:37], v[52:53], v[42:43] op_sel_hi:[0,1]
	v_pk_mul_f32 v[42:43], v[38:39], v[36:37]
	v_cvt_pk_bf16_f32 v36, v44, v45
	v_cvt_pk_bf16_f32 v37, v46, v47
	v_cvt_pk_bf16_f32 v38, v40, v41
	v_cvt_pk_bf16_f32 v39, v42, v43
	s_add_u32 s98, s2, 0x1b8000
	s_addc_u32 s99, s3, 0
	global_store_dwordx4 v246, v[36:39], s[98:99]
	s_nop 1
	v_mul_f32_e32 v37, 0xbfb8aa3b, v189
	v_pk_mul_f32 v[244:245], v[32:33], v[36:37] op_sel:[0,1]
	v_exp_f32_e32 v38, v244
	v_exp_f32_e32 v39, v245
	v_pk_mul_f32 v[40:41], v[34:35], v[36:37] op_sel:[0,1]
	v_exp_f32_e32 v40, v40
	v_exp_f32_e32 v41, v41
	v_pk_add_f32 v[38:39], v[38:39], 1.0 op_sel_hi:[1,0]
	v_rcp_f32_e32 v38, v38
	v_rcp_f32_e32 v39, v39
	v_pk_add_f32 v[34:35], v[40:41], 1.0 op_sel_hi:[1,0]
	v_rcp_f32_e32 v34, v34
	v_rcp_f32_e32 v35, v35
	v_mul_f32_e32 v36, v189, v189
	v_pk_mul_f32 v[32:33], v[36:37], v[38:39] op_sel_hi:[0,1]
	v_pk_mul_f32 v[28:29], v[28:29], v[32:33]
	v_pk_mul_f32 v[32:33], v[36:37], v[34:35] op_sel_hi:[0,1]
	v_pk_mul_f32 v[34:35], v[24:25], v[36:37] op_sel:[0,1]
	v_exp_f32_e32 v34, v34
	v_exp_f32_e32 v35, v35
	v_pk_mul_f32 v[30:31], v[30:31], v[32:33]
	v_pk_add_f32 v[32:33], v[34:35], 1.0 op_sel_hi:[1,0]
	v_pk_mul_f32 v[34:35], v[26:27], v[36:37] op_sel:[0,1]
	v_exp_f32_e32 v34, v34
	v_exp_f32_e32 v35, v35
	v_rcp_f32_e32 v32, v32
	v_rcp_f32_e32 v33, v33
	v_pk_add_f32 v[26:27], v[34:35], 1.0 op_sel_hi:[1,0]
	v_rcp_f32_e32 v26, v26
	v_rcp_f32_e32 v27, v27
	v_pk_mul_f32 v[24:25], v[36:37], v[32:33] op_sel_hi:[0,1]
	v_pk_mul_f32 v[24:25], v[20:21], v[24:25]
	v_pk_mul_f32 v[20:21], v[36:37], v[26:27] op_sel_hi:[0,1]
	v_pk_mul_f32 v[26:27], v[22:23], v[20:21]
	v_cvt_pk_bf16_f32 v20, v28, v29
	v_cvt_pk_bf16_f32 v21, v30, v31
	v_cvt_pk_bf16_f32 v22, v24, v25
	v_cvt_pk_bf16_f32 v23, v26, v27
	s_add_u32 s98, s2, 0x1e4000
	s_addc_u32 s99, s3, 0
	global_store_dwordx4 v246, v[20:23], s[98:99]
	s_mov_b64 s[2:3], -1
	s_cbranch_vccnz .LBB0_252
	s_andn2_b64 vcc, exec, s[0:1]
	s_cbranch_vccnz .LBB0_251
	s_barrier
	s_branch .LBB0_251
